# mixer B kt128 loop rewritten by hand as a software-pipelined loop (PV MFMAs interleaved with next softmax exps, Q fragments resident, fewer LDS reads/nops)
# speedup vs baseline: 1.1543x; 1.1543x over previous
; #define LAS __attribute__((address_space(3)))
; DI void mixerB2_unit(int u, int l, const bf16* PROJ, bf16* YC, const float* dlam_l, const float* dnw_l, const float* kmax_l, LAS char* lds, int tid, int wave, int lane) {
;     ...
;     for (int kt128 = 0; kt128 < 16; ++kt128) {
;         {
;         const LAS char* K0 = Kb + (kt128 & 1) * KV_TILE; const LAS char* V0 = Vb + (kt128 & 1) * KV_TILE;
;     ...
;         SBlk SA, SB;
;         B_QK(SA, 0, 0); B_QK(SB, 0, 1);
;         B_SMPV(SA, 0, 0);
;         if (kt128 + 1 < 16) { const size_t ro = (size_t)(128 * (kt128 + 1) + lrow) * 64 + lch * 8; rk = *(const u32x4*)(kbase + ro); rv = *(const u32x4*)(vbase + ro); }
;         B_QK(SA, 1, 0);
;         B_SMPV(SB, 0, 1);
;         B_QK(SB, 1, 1);
;         if (kt128 + 1 < 16) { LAS char* Kn = Kb + ((kt128 + 1) & 1) * KV_TILE; LAS char* Vn = Vb + ((kt128 + 1) & 1) * KV_TILE;
;             *(LAS u32x4*)(Kn + lrow * KV_PITCH + lch * 16) = rk; *(LAS u32x4*)(Vn + lrow * KV_PITCH + lch * 16) = rv;
;             const size_t ro = (size_t)(128 * (kt128 + 1) + 64 + lrow) * 64 + lch * 8; rk = *(const u32x4*)(kbase + ro); rv = *(const u32x4*)(vbase + ro); }
;         B_SMPV(SA, 1, 0);
;         B_SMPV(SB, 1, 1);
;     ...
;         }
;         if (kt128 + 1 < 16) { LAS char* Kn = Kb + ((kt128 + 1) & 1) * KV_TILE; LAS char* Vn = Vb + ((kt128 + 1) & 1) * KV_TILE;
;             *(LAS u32x4*)(Kn + (lrow + 64) * KV_PITCH + lch * 16) = rk; *(LAS u32x4*)(Vn + (lrow + 64) * KV_PITCH + lch * 16) = rv; }
;         __syncthreads();
;     }
.LBB0_254:
	s_mov_b32 s0, 0
	s_movk_i32 s1, 0x4800
	v_add_u32_e32 v232, v171, v166
	v_add_u32_e32 v250, v198, v199
	v_mov_b32_e32 v218, v232
	v_mov_b32_e32 v217, v250
	ds_read_b128 v[156:159], v213
	ds_read_b128 v[160:163], v213 offset:64
	ds_read_b128 v[242:245], v213 offset:2304
	ds_read_b128 v[246:249], v213 offset:2368
	ds_read_b128 v[140:143], v218
	ds_read_b128 v[144:147], v218 offset:64
	ds_read_b128 v[148:151], v218 offset:2304
	ds_read_b128 v[152:155], v218 offset:2368
	v_mov_b32_e32 v228, 0x3f803f80
	v_mov_b32_e32 v229, 0x3f803f80
	v_mov_b32_e32 v230, 0x3f803f80
	v_mov_b32_e32 v231, 0x3f803f80
	v_mov_b32_e32 v116, 0
	v_mov_b32_e32 v117, 0
	v_mov_b32_e32 v118, 0
	v_mov_b32_e32 v119, 0
	v_mov_b32_e32 v120, 0
	v_mov_b32_e32 v121, 0
	v_mov_b32_e32 v122, 0
	v_mov_b32_e32 v123, 0
	v_mov_b32_e32 v124, 0
	v_mov_b32_e32 v125, 0
	v_mov_b32_e32 v126, 0
	v_mov_b32_e32 v127, 0
	v_mov_b32_e32 v128, 0
	v_mov_b32_e32 v129, 0
	v_mov_b32_e32 v130, 0
	v_mov_b32_e32 v131, 0
	v_mov_b32_e32 v132, 0
	v_mov_b32_e32 v133, 0
	v_mov_b32_e32 v134, 0
	v_mov_b32_e32 v135, 0
	v_mov_b32_e32 v136, 0
	v_mov_b32_e32 v137, 0
	v_mov_b32_e32 v138, 0
	v_mov_b32_e32 v139, 0
	s_add_i32 s40, s44, s46
	s_add_i32 s41, s40, 0
	v_cvt_f32_i32_e32 v225, s41
	v_add_f32_e32 v194, v225, v186
	v_add_f32_e32 v195, v225, v187
	v_add_f32_e32 v196, v225, v191
	v_add_f32_e32 v197, v225, v193
	v_add_f32_e32 v220, 0x41800000, v194
	v_add_f32_e32 v221, 0x41800000, v195
	v_add_f32_e32 v222, 0x41800000, v196
	v_add_f32_e32 v223, 0x41800000, v197
	v_fma_f32 v194, |v194|, v214, v215
	v_fma_f32 v195, |v195|, v214, v215
	v_fma_f32 v196, |v196|, v214, v215
	v_fma_f32 v197, |v197|, v214, v215
	v_fma_f32 v220, |v220|, v214, v215
	v_fma_f32 v221, |v221|, v214, v215
	v_fma_f32 v222, |v222|, v214, v215
	v_fma_f32 v223, |v223|, v214, v215
	s_waitcnt lgkmcnt(3)
	v_mfma_f32_16x16x32_bf16 v[92:95], v[140:143], v[156:159], v[194:197]
	s_waitcnt lgkmcnt(2)
	v_mfma_f32_16x16x32_bf16 v[96:99], v[144:147], v[160:163], v[194:197]
	s_waitcnt lgkmcnt(1)
	v_mfma_f32_16x16x32_bf16 v[100:103], v[148:151], v[156:159], v[220:223]
	s_waitcnt lgkmcnt(0)
	v_mfma_f32_16x16x32_bf16 v[104:107], v[152:155], v[160:163], v[220:223]
	s_sub_i32 s41, s40, 16
	v_cvt_f32_i32_e32 v225, s41
	v_add_f32_e32 v194, v225, v186
	v_add_f32_e32 v195, v225, v187
	v_add_f32_e32 v196, v225, v191
	v_add_f32_e32 v197, v225, v193
	v_add_f32_e32 v220, 0x41800000, v194
	v_add_f32_e32 v221, 0x41800000, v195
	v_add_f32_e32 v222, 0x41800000, v196
	v_add_f32_e32 v223, 0x41800000, v197
	v_fma_f32 v194, |v194|, v214, v216
	v_fma_f32 v195, |v195|, v214, v216
	v_fma_f32 v196, |v196|, v214, v216
	v_fma_f32 v197, |v197|, v214, v216
	v_fma_f32 v220, |v220|, v214, v216
	v_fma_f32 v221, |v221|, v214, v216
	v_fma_f32 v222, |v222|, v214, v216
	v_fma_f32 v223, |v223|, v214, v216
.Lb2_loop:
	v_mfma_f32_16x16x32_bf16 v[52:55], v[228:231], v[116:119], v[52:55]
	v_exp_f32_e32 v92, v92
	v_exp_f32_e32 v93, v93
	v_mfma_f32_16x16x32_bf16 v[48:51], v[228:231], v[120:123], v[48:51]
	v_exp_f32_e32 v94, v94
	v_exp_f32_e32 v95, v95
	v_mfma_f32_16x16x32_bf16 v[44:47], v[124:127], v[116:119], v[44:47]
	v_exp_f32_e32 v100, v100
	v_exp_f32_e32 v101, v101
	v_mfma_f32_16x16x32_bf16 v[32:35], v[124:127], v[120:123], v[32:35]
	v_exp_f32_e32 v102, v102
	v_exp_f32_e32 v103, v103
	v_mfma_f32_16x16x32_bf16 v[40:43], v[128:131], v[116:119], v[40:43]
	v_cvt_pk_bf16_f32 v108, v92, v93
	v_cvt_pk_bf16_f32 v109, v94, v95
	v_cvt_pk_bf16_f32 v110, v100, v101
	v_mfma_f32_16x16x32_bf16 v[24:27], v[128:131], v[120:123], v[24:27]
	v_cvt_pk_bf16_f32 v111, v102, v103
	v_exp_f32_e32 v96, v96
	v_exp_f32_e32 v97, v97
	v_mfma_f32_16x16x32_bf16 v[36:39], v[132:135], v[116:119], v[36:39]
	v_exp_f32_e32 v98, v98
	v_exp_f32_e32 v99, v99
	v_mfma_f32_16x16x32_bf16 v[20:23], v[132:135], v[120:123], v[20:23]
	v_exp_f32_e32 v104, v104
	v_exp_f32_e32 v105, v105
	v_mfma_f32_16x16x32_bf16 v[28:31], v[136:139], v[116:119], v[28:31]
	v_exp_f32_e32 v106, v106
	v_exp_f32_e32 v107, v107
	v_mfma_f32_16x16x32_bf16 v[16:19], v[136:139], v[120:123], v[16:19]
	v_cvt_pk_bf16_f32 v112, v96, v97
	v_cvt_pk_bf16_f32 v113, v98, v99
	v_cvt_pk_bf16_f32 v114, v104, v105
	v_cvt_pk_bf16_f32 v115, v106, v107
	v_mfma_f32_16x16x32_bf16 v[92:95], v[140:143], v[242:245], v[194:197]
	v_mfma_f32_16x16x32_bf16 v[96:99], v[144:147], v[246:249], v[194:197]
	v_mfma_f32_16x16x32_bf16 v[100:103], v[148:151], v[242:245], v[220:223]
	v_mfma_f32_16x16x32_bf16 v[104:107], v[152:155], v[246:249], v[220:223]
	ds_read_b64_tr_b16 v[124:125], v217 offset:36864
	ds_read_b64_tr_b16 v[126:127], v217 offset:39168
	ds_read_b64_tr_b16 v[128:129], v217 offset:36896
	ds_read_b64_tr_b16 v[130:131], v217 offset:39200
	ds_read_b64_tr_b16 v[132:133], v217 offset:36928
	ds_read_b64_tr_b16 v[134:135], v217 offset:39232
	ds_read_b64_tr_b16 v[136:137], v217 offset:36960
	ds_read_b64_tr_b16 v[138:139], v217 offset:39264
	s_cmpk_eq_i32 s46, 0x780
	s_cbranch_scc1 .Lb2_skip1
	v_add_co_u32_e32 v4, vcc, 0xff7fe000, v180
	s_nop 1
	v_addc_co_u32_e32 v5, vcc, -1, v181, vcc
	v_add_co_u32_e32 v8, vcc, 0xffffe000, v180
	s_nop 1
	v_addc_co_u32_e32 v9, vcc, -1, v181, vcc
	global_load_dwordx4 v[4:7], v[4:5], off
	s_nop 0
	global_load_dwordx4 v[8:11], v[8:9], off
; #define LAS __attribute__((address_space(3)))
; DI void mixerB2_unit(int u, int l, const bf16* PROJ, bf16* YC, const float* dlam_l, const float* dnw_l, const float* kmax_l, LAS char* lds, int tid, int wave, int lane) {
;     ...
;     for (int kt128 = 0; kt128 < 16; ++kt128) {
;         {
;         const LAS char* K0 = Kb + (kt128 & 1) * KV_TILE; const LAS char* V0 = Vb + (kt128 & 1) * KV_TILE;
;     ...
;         SBlk SA, SB;
;         B_QK(SA, 0, 0); B_QK(SB, 0, 1);
;         B_SMPV(SA, 0, 0);
;         if (kt128 + 1 < 16) { const size_t ro = (size_t)(128 * (kt128 + 1) + lrow) * 64 + lch * 8; rk = *(const u32x4*)(kbase + ro); rv = *(const u32x4*)(vbase + ro); }
;         B_QK(SA, 1, 0);
;         B_SMPV(SB, 0, 1);
;         B_QK(SB, 1, 1);
;         if (kt128 + 1 < 16) { LAS char* Kn = Kb + ((kt128 + 1) & 1) * KV_TILE; LAS char* Vn = Vb + ((kt128 + 1) & 1) * KV_TILE;
;             *(LAS u32x4*)(Kn + lrow * KV_PITCH + lch * 16) = rk; *(LAS u32x4*)(Vn + lrow * KV_PITCH + lch * 16) = rv;
;             const size_t ro = (size_t)(128 * (kt128 + 1) + 64 + lrow) * 64 + lch * 8; rk = *(const u32x4*)(kbase + ro); rv = *(const u32x4*)(vbase + ro); }
;         B_SMPV(SA, 1, 0);
;         B_SMPV(SB, 1, 1);
.Lb2_skip1:
	s_add_i32 s41, s40, 32
	v_cvt_f32_i32_e32 v225, s41
	v_add_f32_e32 v194, v225, v186
	v_add_f32_e32 v195, v225, v187
	v_add_f32_e32 v196, v225, v191
	v_add_f32_e32 v197, v225, v193
	v_add_f32_e32 v220, 0x41800000, v194
	v_add_f32_e32 v221, 0x41800000, v195
	v_add_f32_e32 v222, 0x41800000, v196
	v_add_f32_e32 v223, 0x41800000, v197
	v_fma_f32 v194, |v194|, v214, v215
	v_fma_f32 v195, |v195|, v214, v215
	v_fma_f32 v196, |v196|, v214, v215
	v_fma_f32 v197, |v197|, v214, v215
	v_fma_f32 v220, |v220|, v214, v215
	v_fma_f32 v221, |v221|, v214, v215
	v_fma_f32 v222, |v222|, v214, v215
	v_fma_f32 v223, |v223|, v214, v215
	ds_read_b128 v[140:143], v218 offset:4608
	ds_read_b128 v[144:147], v218 offset:4672
	ds_read_b128 v[148:151], v218 offset:6912
	ds_read_b128 v[152:155], v218 offset:6976
	v_mfma_f32_16x16x32_bf16 v[88:91], v[228:231], v[108:111], v[88:91]
	v_exp_f32_e32 v92, v92
	v_exp_f32_e32 v93, v93
	v_mfma_f32_16x16x32_bf16 v[84:87], v[228:231], v[112:115], v[84:87]
	v_exp_f32_e32 v94, v94
	v_exp_f32_e32 v95, v95
	s_waitcnt lgkmcnt(10)
	v_mfma_f32_16x16x32_bf16 v[80:83], v[124:127], v[108:111], v[80:83]
	v_exp_f32_e32 v100, v100
	v_exp_f32_e32 v101, v101
	v_mfma_f32_16x16x32_bf16 v[12:15], v[124:127], v[112:115], v[12:15]
	v_exp_f32_e32 v102, v102
	v_exp_f32_e32 v103, v103
	s_waitcnt lgkmcnt(8)
	v_mfma_f32_16x16x32_bf16 v[76:79], v[128:131], v[108:111], v[76:79]
	v_cvt_pk_bf16_f32 v116, v92, v93
	v_cvt_pk_bf16_f32 v117, v94, v95
	v_cvt_pk_bf16_f32 v118, v100, v101
	v_mfma_f32_16x16x32_bf16 v[64:67], v[128:131], v[112:115], v[64:67]
	v_cvt_pk_bf16_f32 v119, v102, v103
	v_exp_f32_e32 v96, v96
	v_exp_f32_e32 v97, v97
	s_waitcnt lgkmcnt(6)
	v_mfma_f32_16x16x32_bf16 v[72:75], v[132:135], v[108:111], v[72:75]
	v_exp_f32_e32 v98, v98
	v_exp_f32_e32 v99, v99
	v_mfma_f32_16x16x32_bf16 v[60:63], v[132:135], v[112:115], v[60:63]
	v_exp_f32_e32 v104, v104
	v_exp_f32_e32 v105, v105
	s_waitcnt lgkmcnt(4)
	v_mfma_f32_16x16x32_bf16 v[68:71], v[136:139], v[108:111], v[68:71]
	v_exp_f32_e32 v106, v106
	v_exp_f32_e32 v107, v107
	v_mfma_f32_16x16x32_bf16 v[56:59], v[136:139], v[112:115], v[56:59]
	v_cvt_pk_bf16_f32 v120, v96, v97
	v_cvt_pk_bf16_f32 v121, v98, v99
	v_cvt_pk_bf16_f32 v122, v104, v105
	v_cvt_pk_bf16_f32 v123, v106, v107
	s_waitcnt lgkmcnt(3)
	v_mfma_f32_16x16x32_bf16 v[92:95], v[140:143], v[156:159], v[194:197]
	s_waitcnt lgkmcnt(2)
	v_mfma_f32_16x16x32_bf16 v[96:99], v[144:147], v[160:163], v[194:197]
	s_waitcnt lgkmcnt(1)
	v_mfma_f32_16x16x32_bf16 v[100:103], v[148:151], v[156:159], v[220:223]
	s_waitcnt lgkmcnt(0)
	v_mfma_f32_16x16x32_bf16 v[104:107], v[152:155], v[160:163], v[220:223]
	s_add_i32 s41, s40, 16
	v_cvt_f32_i32_e32 v225, s41
	v_add_f32_e32 v194, v225, v186
	v_add_f32_e32 v195, v225, v187
	v_add_f32_e32 v196, v225, v191
	v_add_f32_e32 v197, v225, v193
	v_add_f32_e32 v220, 0x41800000, v194
	v_add_f32_e32 v221, 0x41800000, v195
	v_add_f32_e32 v222, 0x41800000, v196
	v_add_f32_e32 v223, 0x41800000, v197
	v_fma_f32 v194, |v194|, v214, v216
	v_fma_f32 v195, |v195|, v214, v216
	v_fma_f32 v196, |v196|, v214, v216
	v_fma_f32 v197, |v197|, v214, v216
	v_fma_f32 v220, |v220|, v214, v216
	v_fma_f32 v221, |v221|, v214, v216
	v_fma_f32 v222, |v222|, v214, v216
	v_fma_f32 v223, |v223|, v214, v216
	v_mfma_f32_16x16x32_bf16 v[52:55], v[228:231], v[116:119], v[52:55]
	v_exp_f32_e32 v92, v92
	v_exp_f32_e32 v93, v93
	v_mfma_f32_16x16x32_bf16 v[48:51], v[228:231], v[120:123], v[48:51]
	v_exp_f32_e32 v94, v94
	v_exp_f32_e32 v95, v95
	v_mfma_f32_16x16x32_bf16 v[44:47], v[124:127], v[116:119], v[44:47]
	v_exp_f32_e32 v100, v100
	v_exp_f32_e32 v101, v101
	v_mfma_f32_16x16x32_bf16 v[32:35], v[124:127], v[120:123], v[32:35]
	v_exp_f32_e32 v102, v102
	v_exp_f32_e32 v103, v103
	v_mfma_f32_16x16x32_bf16 v[40:43], v[128:131], v[116:119], v[40:43]
	v_cvt_pk_bf16_f32 v108, v92, v93
	v_cvt_pk_bf16_f32 v109, v94, v95
	v_cvt_pk_bf16_f32 v110, v100, v101
	v_mfma_f32_16x16x32_bf16 v[24:27], v[128:131], v[120:123], v[24:27]
	v_cvt_pk_bf16_f32 v111, v102, v103
	v_exp_f32_e32 v96, v96
	v_exp_f32_e32 v97, v97
	v_mfma_f32_16x16x32_bf16 v[36:39], v[132:135], v[116:119], v[36:39]
	v_exp_f32_e32 v98, v98
	v_exp_f32_e32 v99, v99
	v_mfma_f32_16x16x32_bf16 v[20:23], v[132:135], v[120:123], v[20:23]
	v_exp_f32_e32 v104, v104
	v_exp_f32_e32 v105, v105
	v_mfma_f32_16x16x32_bf16 v[28:31], v[136:139], v[116:119], v[28:31]
	v_exp_f32_e32 v106, v106
	v_exp_f32_e32 v107, v107
	v_mfma_f32_16x16x32_bf16 v[16:19], v[136:139], v[120:123], v[16:19]
	v_cvt_pk_bf16_f32 v112, v96, v97
	v_cvt_pk_bf16_f32 v113, v98, v99
	v_cvt_pk_bf16_f32 v114, v104, v105
	v_cvt_pk_bf16_f32 v115, v106, v107
	v_mfma_f32_16x16x32_bf16 v[92:95], v[140:143], v[242:245], v[194:197]
	v_mfma_f32_16x16x32_bf16 v[96:99], v[144:147], v[246:249], v[194:197]
	v_mfma_f32_16x16x32_bf16 v[100:103], v[148:151], v[242:245], v[220:223]
	v_mfma_f32_16x16x32_bf16 v[104:107], v[152:155], v[246:249], v[220:223]
	ds_read_b64_tr_b16 v[124:125], v217 offset:41472
	ds_read_b64_tr_b16 v[126:127], v217 offset:43776
	ds_read_b64_tr_b16 v[128:129], v217 offset:41504
	ds_read_b64_tr_b16 v[130:131], v217 offset:43808
	ds_read_b64_tr_b16 v[132:133], v217 offset:41536
	ds_read_b64_tr_b16 v[134:135], v217 offset:43840
	ds_read_b64_tr_b16 v[136:137], v217 offset:41568
	ds_read_b64_tr_b16 v[138:139], v217 offset:43872
	s_add_i32 s41, s40, 64
	v_cvt_f32_i32_e32 v225, s41
	v_add_f32_e32 v194, v225, v186
	v_add_f32_e32 v195, v225, v187
	v_add_f32_e32 v196, v225, v191
	v_add_f32_e32 v197, v225, v193
	v_add_f32_e32 v220, 0x41800000, v194
	v_add_f32_e32 v221, 0x41800000, v195
	v_add_f32_e32 v222, 0x41800000, v196
	v_add_f32_e32 v223, 0x41800000, v197
	v_fma_f32 v194, |v194|, v214, v215
	v_fma_f32 v195, |v195|, v214, v215
	v_fma_f32 v196, |v196|, v214, v215
	v_fma_f32 v197, |v197|, v214, v215
	v_fma_f32 v220, |v220|, v214, v215
	v_fma_f32 v221, |v221|, v214, v215
	v_fma_f32 v222, |v222|, v214, v215
	v_fma_f32 v223, |v223|, v214, v215
	ds_read_b128 v[140:143], v218 offset:9216
	ds_read_b128 v[144:147], v218 offset:9280
	ds_read_b128 v[148:151], v218 offset:11520
	ds_read_b128 v[152:155], v218 offset:11584
	v_mfma_f32_16x16x32_bf16 v[88:91], v[228:231], v[108:111], v[88:91]
	v_exp_f32_e32 v92, v92
	v_exp_f32_e32 v93, v93
	v_mfma_f32_16x16x32_bf16 v[84:87], v[228:231], v[112:115], v[84:87]
	v_exp_f32_e32 v94, v94
	v_exp_f32_e32 v95, v95
	s_waitcnt lgkmcnt(10)
; #define LAS __attribute__((address_space(3)))
; DI void mixerB2_unit(int u, int l, const bf16* PROJ, bf16* YC, const float* dlam_l, const float* dnw_l, const float* kmax_l, LAS char* lds, int tid, int wave, int lane) {
;     ...
;         if (kt128 + 1 < 16) { const size_t ro = (size_t)(128 * (kt128 + 1) + lrow) * 64 + lch * 8; rk = *(const u32x4*)(kbase + ro); rv = *(const u32x4*)(vbase + ro); }
;         B_QK(SA, 1, 0);
;         B_SMPV(SB, 0, 1);
;         B_QK(SB, 1, 1);
;         if (kt128 + 1 < 16) { LAS char* Kn = Kb + ((kt128 + 1) & 1) * KV_TILE; LAS char* Vn = Vb + ((kt128 + 1) & 1) * KV_TILE;
;             *(LAS u32x4*)(Kn + lrow * KV_PITCH + lch * 16) = rk; *(LAS u32x4*)(Vn + lrow * KV_PITCH + lch * 16) = rv;
;             const size_t ro = (size_t)(128 * (kt128 + 1) + 64 + lrow) * 64 + lch * 8; rk = *(const u32x4*)(kbase + ro); rv = *(const u32x4*)(vbase + ro); }
;         B_SMPV(SA, 1, 0);
	v_mfma_f32_16x16x32_bf16 v[80:83], v[124:127], v[108:111], v[80:83]
	v_exp_f32_e32 v100, v100
	v_exp_f32_e32 v101, v101
	v_mfma_f32_16x16x32_bf16 v[12:15], v[124:127], v[112:115], v[12:15]
	v_exp_f32_e32 v102, v102
	v_exp_f32_e32 v103, v103
	s_waitcnt lgkmcnt(8)
	v_mfma_f32_16x16x32_bf16 v[76:79], v[128:131], v[108:111], v[76:79]
	v_cvt_pk_bf16_f32 v116, v92, v93
	v_cvt_pk_bf16_f32 v117, v94, v95
	v_cvt_pk_bf16_f32 v118, v100, v101
	v_mfma_f32_16x16x32_bf16 v[64:67], v[128:131], v[112:115], v[64:67]
	v_cvt_pk_bf16_f32 v119, v102, v103
	v_exp_f32_e32 v96, v96
	v_exp_f32_e32 v97, v97
	s_waitcnt lgkmcnt(6)
	v_mfma_f32_16x16x32_bf16 v[72:75], v[132:135], v[108:111], v[72:75]
	v_exp_f32_e32 v98, v98
	v_exp_f32_e32 v99, v99
	v_mfma_f32_16x16x32_bf16 v[60:63], v[132:135], v[112:115], v[60:63]
	v_exp_f32_e32 v104, v104
	v_exp_f32_e32 v105, v105
	s_waitcnt lgkmcnt(4)
	v_mfma_f32_16x16x32_bf16 v[68:71], v[136:139], v[108:111], v[68:71]
	v_exp_f32_e32 v106, v106
	v_exp_f32_e32 v107, v107
	v_mfma_f32_16x16x32_bf16 v[56:59], v[136:139], v[112:115], v[56:59]
	v_cvt_pk_bf16_f32 v120, v96, v97
	v_cvt_pk_bf16_f32 v121, v98, v99
	v_cvt_pk_bf16_f32 v122, v104, v105
	v_cvt_pk_bf16_f32 v123, v106, v107
	s_waitcnt lgkmcnt(3)
	v_mfma_f32_16x16x32_bf16 v[92:95], v[140:143], v[156:159], v[194:197]
	s_waitcnt lgkmcnt(2)
	v_mfma_f32_16x16x32_bf16 v[96:99], v[144:147], v[160:163], v[194:197]
	s_waitcnt lgkmcnt(1)
	v_mfma_f32_16x16x32_bf16 v[100:103], v[148:151], v[156:159], v[220:223]
	s_waitcnt lgkmcnt(0)
	v_mfma_f32_16x16x32_bf16 v[104:107], v[152:155], v[160:163], v[220:223]
	s_cmpk_eq_i32 s46, 0x780
	s_cbranch_scc1 .Lb2_skip2
	v_add_u32_e32 v219, s1, v182
	s_waitcnt vmcnt(1)
	ds_write_b128 v219, v[4:7]
	s_waitcnt vmcnt(0)
	ds_write_b128 v219, v[8:11] offset:36864
	v_add_co_u32_e32 v4, vcc, 0xff800000, v180
	s_nop 1
	v_addc_co_u32_e32 v5, vcc, -1, v181, vcc
	global_load_dwordx4 v[4:7], v[4:5], off
	s_nop 0
	global_load_dwordx4 v[8:11], v[180:181], off
.Lb2_skip2:
	s_add_i32 s41, s40, 48
	v_cvt_f32_i32_e32 v225, s41
	v_add_f32_e32 v194, v225, v186
	v_add_f32_e32 v195, v225, v187
	v_add_f32_e32 v196, v225, v191
	v_add_f32_e32 v197, v225, v193
	v_add_f32_e32 v220, 0x41800000, v194
	v_add_f32_e32 v221, 0x41800000, v195
	v_add_f32_e32 v222, 0x41800000, v196
	v_add_f32_e32 v223, 0x41800000, v197
	v_fma_f32 v194, |v194|, v214, v216
	v_fma_f32 v195, |v195|, v214, v216
	v_fma_f32 v196, |v196|, v214, v216
	v_fma_f32 v197, |v197|, v214, v216
	v_fma_f32 v220, |v220|, v214, v216
	v_fma_f32 v221, |v221|, v214, v216
	v_fma_f32 v222, |v222|, v214, v216
	v_fma_f32 v223, |v223|, v214, v216
	v_mfma_f32_16x16x32_bf16 v[52:55], v[228:231], v[116:119], v[52:55]
	v_exp_f32_e32 v92, v92
	v_exp_f32_e32 v93, v93
	v_mfma_f32_16x16x32_bf16 v[48:51], v[228:231], v[120:123], v[48:51]
	v_exp_f32_e32 v94, v94
	v_exp_f32_e32 v95, v95
	v_mfma_f32_16x16x32_bf16 v[44:47], v[124:127], v[116:119], v[44:47]
	v_exp_f32_e32 v100, v100
	v_exp_f32_e32 v101, v101
	v_mfma_f32_16x16x32_bf16 v[32:35], v[124:127], v[120:123], v[32:35]
	v_exp_f32_e32 v102, v102
	v_exp_f32_e32 v103, v103
	v_mfma_f32_16x16x32_bf16 v[40:43], v[128:131], v[116:119], v[40:43]
	v_cvt_pk_bf16_f32 v108, v92, v93
	v_cvt_pk_bf16_f32 v109, v94, v95
	v_cvt_pk_bf16_f32 v110, v100, v101
	v_mfma_f32_16x16x32_bf16 v[24:27], v[128:131], v[120:123], v[24:27]
	v_cvt_pk_bf16_f32 v111, v102, v103
	v_exp_f32_e32 v96, v96
	v_exp_f32_e32 v97, v97
	v_mfma_f32_16x16x32_bf16 v[36:39], v[132:135], v[116:119], v[36:39]
	v_exp_f32_e32 v98, v98
	v_exp_f32_e32 v99, v99
	v_mfma_f32_16x16x32_bf16 v[20:23], v[132:135], v[120:123], v[20:23]
	v_exp_f32_e32 v104, v104
	v_exp_f32_e32 v105, v105
	v_mfma_f32_16x16x32_bf16 v[28:31], v[136:139], v[116:119], v[28:31]
	v_exp_f32_e32 v106, v106
	v_exp_f32_e32 v107, v107
	v_mfma_f32_16x16x32_bf16 v[16:19], v[136:139], v[120:123], v[16:19]
	v_cvt_pk_bf16_f32 v112, v96, v97
	v_cvt_pk_bf16_f32 v113, v98, v99
	v_cvt_pk_bf16_f32 v114, v104, v105
	v_cvt_pk_bf16_f32 v115, v106, v107
	v_mfma_f32_16x16x32_bf16 v[92:95], v[140:143], v[242:245], v[194:197]
	v_mfma_f32_16x16x32_bf16 v[96:99], v[144:147], v[246:249], v[194:197]
	v_mfma_f32_16x16x32_bf16 v[100:103], v[148:151], v[242:245], v[220:223]
	v_mfma_f32_16x16x32_bf16 v[104:107], v[152:155], v[246:249], v[220:223]
	ds_read_b64_tr_b16 v[124:125], v217 offset:46080
	ds_read_b64_tr_b16 v[126:127], v217 offset:48384
	ds_read_b64_tr_b16 v[128:129], v217 offset:46112
	ds_read_b64_tr_b16 v[130:131], v217 offset:48416
	ds_read_b64_tr_b16 v[132:133], v217 offset:46144
	ds_read_b64_tr_b16 v[134:135], v217 offset:48448
	ds_read_b64_tr_b16 v[136:137], v217 offset:46176
	ds_read_b64_tr_b16 v[138:139], v217 offset:48480
	s_add_i32 s41, s40, 96
	v_cvt_f32_i32_e32 v225, s41
	v_add_f32_e32 v194, v225, v186
	v_add_f32_e32 v195, v225, v187
	v_add_f32_e32 v196, v225, v191
	v_add_f32_e32 v197, v225, v193
	v_add_f32_e32 v220, 0x41800000, v194
	v_add_f32_e32 v221, 0x41800000, v195
	v_add_f32_e32 v222, 0x41800000, v196
	v_add_f32_e32 v223, 0x41800000, v197
	v_fma_f32 v194, |v194|, v214, v215
	v_fma_f32 v195, |v195|, v214, v215
	v_fma_f32 v196, |v196|, v214, v215
	v_fma_f32 v197, |v197|, v214, v215
	v_fma_f32 v220, |v220|, v214, v215
	v_fma_f32 v221, |v221|, v214, v215
	v_fma_f32 v222, |v222|, v214, v215
	v_fma_f32 v223, |v223|, v214, v215
	ds_read_b128 v[140:143], v218 offset:13824
	ds_read_b128 v[144:147], v218 offset:13888
	ds_read_b128 v[148:151], v218 offset:16128
	ds_read_b128 v[152:155], v218 offset:16192
	v_mfma_f32_16x16x32_bf16 v[88:91], v[228:231], v[108:111], v[88:91]
	v_exp_f32_e32 v92, v92
	v_exp_f32_e32 v93, v93
	v_mfma_f32_16x16x32_bf16 v[84:87], v[228:231], v[112:115], v[84:87]
	v_exp_f32_e32 v94, v94
	v_exp_f32_e32 v95, v95
	s_waitcnt lgkmcnt(10)
; #define LAS __attribute__((address_space(3)))
; DI void mixerB2_unit(int u, int l, const bf16* PROJ, bf16* YC, const float* dlam_l, const float* dnw_l, const float* kmax_l, LAS char* lds, int tid, int wave, int lane) {
;     ...
;         if (kt128 + 1 < 16) { LAS char* Kn = Kb + ((kt128 + 1) & 1) * KV_TILE; LAS char* Vn = Vb + ((kt128 + 1) & 1) * KV_TILE;
;             *(LAS u32x4*)(Kn + (lrow + 64) * KV_PITCH + lch * 16) = rk; *(LAS u32x4*)(Vn + (lrow + 64) * KV_PITCH + lch * 16) = rv; }
	v_mfma_f32_16x16x32_bf16 v[80:83], v[124:127], v[108:111], v[80:83]
	v_exp_f32_e32 v100, v100
	v_exp_f32_e32 v101, v101
	v_mfma_f32_16x16x32_bf16 v[12:15], v[124:127], v[112:115], v[12:15]
	v_exp_f32_e32 v102, v102
	v_exp_f32_e32 v103, v103
	s_waitcnt lgkmcnt(8)
	v_mfma_f32_16x16x32_bf16 v[76:79], v[128:131], v[108:111], v[76:79]
	v_cvt_pk_bf16_f32 v116, v92, v93
	v_cvt_pk_bf16_f32 v117, v94, v95
	v_cvt_pk_bf16_f32 v118, v100, v101
	v_mfma_f32_16x16x32_bf16 v[64:67], v[128:131], v[112:115], v[64:67]
	v_cvt_pk_bf16_f32 v119, v102, v103
	v_exp_f32_e32 v96, v96
	v_exp_f32_e32 v97, v97
	s_waitcnt lgkmcnt(6)
	v_mfma_f32_16x16x32_bf16 v[72:75], v[132:135], v[108:111], v[72:75]
	v_exp_f32_e32 v98, v98
	v_exp_f32_e32 v99, v99
	v_mfma_f32_16x16x32_bf16 v[60:63], v[132:135], v[112:115], v[60:63]
	v_exp_f32_e32 v104, v104
	v_exp_f32_e32 v105, v105
	s_waitcnt lgkmcnt(4)
	v_mfma_f32_16x16x32_bf16 v[68:71], v[136:139], v[108:111], v[68:71]
	v_exp_f32_e32 v106, v106
	v_exp_f32_e32 v107, v107
	v_mfma_f32_16x16x32_bf16 v[56:59], v[136:139], v[112:115], v[56:59]
	v_cvt_pk_bf16_f32 v120, v96, v97
	v_cvt_pk_bf16_f32 v121, v98, v99
	v_cvt_pk_bf16_f32 v122, v104, v105
	v_cvt_pk_bf16_f32 v123, v106, v107
	s_waitcnt lgkmcnt(3)
	v_mfma_f32_16x16x32_bf16 v[92:95], v[140:143], v[156:159], v[194:197]
	s_waitcnt lgkmcnt(2)
	v_mfma_f32_16x16x32_bf16 v[96:99], v[144:147], v[160:163], v[194:197]
	s_waitcnt lgkmcnt(1)
	v_mfma_f32_16x16x32_bf16 v[100:103], v[148:151], v[156:159], v[220:223]
	s_waitcnt lgkmcnt(0)
	v_mfma_f32_16x16x32_bf16 v[104:107], v[152:155], v[160:163], v[220:223]
	s_add_i32 s41, s40, 80
	v_cvt_f32_i32_e32 v225, s41
	v_add_f32_e32 v194, v225, v186
	v_add_f32_e32 v195, v225, v187
	v_add_f32_e32 v196, v225, v191
	v_add_f32_e32 v197, v225, v193
	v_add_f32_e32 v220, 0x41800000, v194
	v_add_f32_e32 v221, 0x41800000, v195
	v_add_f32_e32 v222, 0x41800000, v196
	v_add_f32_e32 v223, 0x41800000, v197
	v_fma_f32 v194, |v194|, v214, v216
	v_fma_f32 v195, |v195|, v214, v216
	v_fma_f32 v196, |v196|, v214, v216
	v_fma_f32 v197, |v197|, v214, v216
	v_fma_f32 v220, |v220|, v214, v216
	v_fma_f32 v221, |v221|, v214, v216
	v_fma_f32 v222, |v222|, v214, v216
	v_fma_f32 v223, |v223|, v214, v216
	v_mfma_f32_16x16x32_bf16 v[52:55], v[228:231], v[116:119], v[52:55]
	v_exp_f32_e32 v92, v92
	v_exp_f32_e32 v93, v93
	v_mfma_f32_16x16x32_bf16 v[48:51], v[228:231], v[120:123], v[48:51]
	v_exp_f32_e32 v94, v94
	v_exp_f32_e32 v95, v95
	v_mfma_f32_16x16x32_bf16 v[44:47], v[124:127], v[116:119], v[44:47]
	v_exp_f32_e32 v100, v100
	v_exp_f32_e32 v101, v101
	v_mfma_f32_16x16x32_bf16 v[32:35], v[124:127], v[120:123], v[32:35]
	v_exp_f32_e32 v102, v102
	v_exp_f32_e32 v103, v103
	v_mfma_f32_16x16x32_bf16 v[40:43], v[128:131], v[116:119], v[40:43]
	v_cvt_pk_bf16_f32 v108, v92, v93
	v_cvt_pk_bf16_f32 v109, v94, v95
	v_cvt_pk_bf16_f32 v110, v100, v101
	v_mfma_f32_16x16x32_bf16 v[24:27], v[128:131], v[120:123], v[24:27]
	v_cvt_pk_bf16_f32 v111, v102, v103
	v_exp_f32_e32 v96, v96
	v_exp_f32_e32 v97, v97
	v_mfma_f32_16x16x32_bf16 v[36:39], v[132:135], v[116:119], v[36:39]
	v_exp_f32_e32 v98, v98
	v_exp_f32_e32 v99, v99
	v_mfma_f32_16x16x32_bf16 v[20:23], v[132:135], v[120:123], v[20:23]
	v_exp_f32_e32 v104, v104
	v_exp_f32_e32 v105, v105
	v_mfma_f32_16x16x32_bf16 v[28:31], v[136:139], v[116:119], v[28:31]
	v_exp_f32_e32 v106, v106
	v_exp_f32_e32 v107, v107
	v_mfma_f32_16x16x32_bf16 v[16:19], v[136:139], v[120:123], v[16:19]
	v_cvt_pk_bf16_f32 v112, v96, v97
	v_cvt_pk_bf16_f32 v113, v98, v99
	v_cvt_pk_bf16_f32 v114, v104, v105
	v_cvt_pk_bf16_f32 v115, v106, v107
	v_mfma_f32_16x16x32_bf16 v[92:95], v[140:143], v[242:245], v[194:197]
	v_mfma_f32_16x16x32_bf16 v[96:99], v[144:147], v[246:249], v[194:197]
	v_mfma_f32_16x16x32_bf16 v[100:103], v[148:151], v[242:245], v[220:223]
	v_mfma_f32_16x16x32_bf16 v[104:107], v[152:155], v[246:249], v[220:223]
	ds_read_b64_tr_b16 v[124:125], v217 offset:50688
	ds_read_b64_tr_b16 v[126:127], v217 offset:52992
	ds_read_b64_tr_b16 v[128:129], v217 offset:50720
	ds_read_b64_tr_b16 v[130:131], v217 offset:53024
	ds_read_b64_tr_b16 v[132:133], v217 offset:50752
	ds_read_b64_tr_b16 v[134:135], v217 offset:53056
	ds_read_b64_tr_b16 v[136:137], v217 offset:50784
	ds_read_b64_tr_b16 v[138:139], v217 offset:53088
	s_add_i32 s41, s40, 128
	v_cvt_f32_i32_e32 v225, s41
	v_add_f32_e32 v194, v225, v186
	v_add_f32_e32 v195, v225, v187
	v_add_f32_e32 v196, v225, v191
	v_add_f32_e32 v197, v225, v193
	v_add_f32_e32 v220, 0x41800000, v194
	v_add_f32_e32 v221, 0x41800000, v195
	v_add_f32_e32 v222, 0x41800000, v196
	v_add_f32_e32 v223, 0x41800000, v197
	v_fma_f32 v194, |v194|, v214, v215
	v_fma_f32 v195, |v195|, v214, v215
	v_fma_f32 v196, |v196|, v214, v215
	v_fma_f32 v197, |v197|, v214, v215
	v_fma_f32 v220, |v220|, v214, v215
	v_fma_f32 v221, |v221|, v214, v215
	v_fma_f32 v222, |v222|, v214, v215
	v_fma_f32 v223, |v223|, v214, v215
	v_mfma_f32_16x16x32_bf16 v[88:91], v[228:231], v[108:111], v[88:91]
	v_exp_f32_e32 v92, v92
	v_exp_f32_e32 v93, v93
	v_mfma_f32_16x16x32_bf16 v[84:87], v[228:231], v[112:115], v[84:87]
	v_exp_f32_e32 v94, v94
	v_exp_f32_e32 v95, v95
	s_waitcnt lgkmcnt(6)
	v_mfma_f32_16x16x32_bf16 v[80:83], v[124:127], v[108:111], v[80:83]
	v_exp_f32_e32 v100, v100
	v_exp_f32_e32 v101, v101
	v_mfma_f32_16x16x32_bf16 v[12:15], v[124:127], v[112:115], v[12:15]
	v_exp_f32_e32 v102, v102
	v_exp_f32_e32 v103, v103
	s_waitcnt lgkmcnt(4)
	v_mfma_f32_16x16x32_bf16 v[76:79], v[128:131], v[108:111], v[76:79]
	v_cvt_pk_bf16_f32 v116, v92, v93
	v_cvt_pk_bf16_f32 v117, v94, v95
	v_cvt_pk_bf16_f32 v118, v100, v101
	s_cmpk_eq_i32 s46, 0x780
	s_cbranch_scc1 .Lb2_skip3
	v_add_u32_e32 v219, s1, v183
	s_waitcnt vmcnt(1)
	ds_write_b128 v219, v[4:7]
	s_waitcnt vmcnt(0)
	ds_write_b128 v219, v[8:11] offset:36864
	v_add_co_u32_e32 v180, vcc, 0x4000, v180
	s_nop 1
	v_addc_co_u32_e32 v181, vcc, 0, v181, vcc
; #define LAS __attribute__((address_space(3)))
; DI void mixerB2_unit(int u, int l, const bf16* PROJ, bf16* YC, const float* dlam_l, const float* dnw_l, const float* kmax_l, LAS char* lds, int tid, int wave, int lane) {
;     ...
;     for (int kt128 = 0; kt128 < 16; ++kt128) {
;         {
;         const LAS char* K0 = Kb + (kt128 & 1) * KV_TILE; const LAS char* V0 = Vb + (kt128 & 1) * KV_TILE;
;     ...
;         SBlk SA, SB;
;         B_QK(SA, 0, 0); B_QK(SB, 0, 1);
;         B_SMPV(SA, 0, 0);
;         if (kt128 + 1 < 16) { const size_t ro = (size_t)(128 * (kt128 + 1) + lrow) * 64 + lch * 8; rk = *(const u32x4*)(kbase + ro); rv = *(const u32x4*)(vbase + ro); }
;         B_QK(SA, 1, 0);
;         B_SMPV(SB, 0, 1);
;         B_QK(SB, 1, 1);
;         if (kt128 + 1 < 16) { LAS char* Kn = Kb + ((kt128 + 1) & 1) * KV_TILE; LAS char* Vn = Vb + ((kt128 + 1) & 1) * KV_TILE;
;             *(LAS u32x4*)(Kn + lrow * KV_PITCH + lch * 16) = rk; *(LAS u32x4*)(Vn + lrow * KV_PITCH + lch * 16) = rv;
;             const size_t ro = (size_t)(128 * (kt128 + 1) + 64 + lrow) * 64 + lch * 8; rk = *(const u32x4*)(kbase + ro); rv = *(const u32x4*)(vbase + ro); }
;         B_SMPV(SA, 1, 0);
;         B_SMPV(SB, 1, 1);
;     ...
;         __syncthreads();
.Lb2_skip3:
	s_waitcnt lgkmcnt(0)
	s_barrier
	s_xor_b32 s0, s0, 0x4800
	s_xor_b32 s1, s1, 0x4800
	s_addk_i32 s46, 0x80
	s_add_i32 s45, s45, 1
	v_add_u32_e32 v218, s0, v232
	v_add_u32_e32 v217, s0, v250
	s_add_i32 s40, s44, s46
	ds_read_b128 v[140:143], v218
	ds_read_b128 v[144:147], v218 offset:64
	ds_read_b128 v[148:151], v218 offset:2304
	ds_read_b128 v[152:155], v218 offset:2368
	v_mfma_f32_16x16x32_bf16 v[64:67], v[128:131], v[112:115], v[64:67]
	v_cvt_pk_bf16_f32 v119, v102, v103
	v_exp_f32_e32 v96, v96
	v_exp_f32_e32 v97, v97
	v_mfma_f32_16x16x32_bf16 v[72:75], v[132:135], v[108:111], v[72:75]
	v_exp_f32_e32 v98, v98
	v_exp_f32_e32 v99, v99
	v_mfma_f32_16x16x32_bf16 v[60:63], v[132:135], v[112:115], v[60:63]
	v_exp_f32_e32 v104, v104
	v_exp_f32_e32 v105, v105
	v_mfma_f32_16x16x32_bf16 v[68:71], v[136:139], v[108:111], v[68:71]
	v_exp_f32_e32 v106, v106
	v_exp_f32_e32 v107, v107
	v_mfma_f32_16x16x32_bf16 v[56:59], v[136:139], v[112:115], v[56:59]
	v_cvt_pk_bf16_f32 v120, v96, v97
	v_cvt_pk_bf16_f32 v121, v98, v99
	v_cvt_pk_bf16_f32 v122, v104, v105
	v_cvt_pk_bf16_f32 v123, v106, v107
	s_cmpk_eq_i32 s46, 0x800
	s_cbranch_scc1 .Lb2_drain
	s_waitcnt lgkmcnt(3)
	v_mfma_f32_16x16x32_bf16 v[92:95], v[140:143], v[156:159], v[194:197]
	s_waitcnt lgkmcnt(2)
	v_mfma_f32_16x16x32_bf16 v[96:99], v[144:147], v[160:163], v[194:197]
	s_waitcnt lgkmcnt(1)
	v_mfma_f32_16x16x32_bf16 v[100:103], v[148:151], v[156:159], v[220:223]
	s_waitcnt lgkmcnt(0)
	v_mfma_f32_16x16x32_bf16 v[104:107], v[152:155], v[160:163], v[220:223]
	s_sub_i32 s41, s40, 16
	v_cvt_f32_i32_e32 v225, s41
	v_add_f32_e32 v194, v225, v186
	v_add_f32_e32 v195, v225, v187
	v_add_f32_e32 v196, v225, v191
	v_add_f32_e32 v197, v225, v193
	v_add_f32_e32 v220, 0x41800000, v194
	v_add_f32_e32 v221, 0x41800000, v195
	v_add_f32_e32 v222, 0x41800000, v196
	v_add_f32_e32 v223, 0x41800000, v197
	v_fma_f32 v194, |v194|, v214, v216
	v_fma_f32 v195, |v195|, v214, v216
	v_fma_f32 v196, |v196|, v214, v216
	v_fma_f32 v197, |v197|, v214, v216
	v_fma_f32 v220, |v220|, v214, v216
	v_fma_f32 v221, |v221|, v214, v216
	v_fma_f32 v222, |v222|, v214, v216
	v_fma_f32 v223, |v223|, v214, v216
	s_branch .Lb2_loop
.Lb2_drain:
	s_waitcnt lgkmcnt(0)
	v_mfma_f32_16x16x32_bf16 v[52:55], v[228:231], v[116:119], v[52:55]
	v_mfma_f32_16x16x32_bf16 v[48:51], v[228:231], v[120:123], v[48:51]
	v_mfma_f32_16x16x32_bf16 v[44:47], v[124:127], v[116:119], v[44:47]
	v_mfma_f32_16x16x32_bf16 v[32:35], v[124:127], v[120:123], v[32:35]
	v_mfma_f32_16x16x32_bf16 v[40:43], v[128:131], v[116:119], v[40:43]
	v_mfma_f32_16x16x32_bf16 v[24:27], v[128:131], v[120:123], v[24:27]
	v_mfma_f32_16x16x32_bf16 v[36:39], v[132:135], v[116:119], v[36:39]
	v_mfma_f32_16x16x32_bf16 v[20:23], v[132:135], v[120:123], v[20:23]
	v_mfma_f32_16x16x32_bf16 v[28:31], v[136:139], v[116:119], v[28:31]
	v_mfma_f32_16x16x32_bf16 v[16:19], v[136:139], v[120:123], v[16:19]
	s_mov_b32 s47, 0
	s_nop 7
